# memory-attention phases: odd workgroups process their two sample units (HBM K/V stream) before the prompt unit so streaming overlaps the other half's compute; last grid barrier removed
# speedup vs baseline: 1.0025x; 1.0017x over previous
; __global__ void __launch_bounds__(NTHR, 2) fwd_megakernel(Params p) {
;     ...
;         { PHASE_IDS
;         for (int rep = 0; rep < REP_LIGHT * REP_MEM; ++rep)
;         for (int u = bx; u < 256 + 512; u += G) { if (u < 256) mem_unit<false>(p, l, lds, u, tid, wave, lane); else mem_unit<true>(p, l, lds, u - 256, tid, wave, lane); } }
.LBB0_594:
	s_or_b64 exec, exec, s[0:1]
	v_readlane_b32 s0, v240, 14
	s_waitcnt lgkmcnt(0)
	v_mov_b32_e32 v0, v216
	v_readlane_b32 s1, v240, 15
	s_barrier
	s_and_b64 vcc, exec, s[0:1]
	v_readfirstlane_b32 s0, v0
	s_cbranch_vccnz .LBB0_633
	s_cmp_lt_u32 s0, 64
	s_cselect_b64 s[4:5], -1, 0
	s_ashr_i32 s0, s0, 2
	s_and_b32 s6, s0, -16
	s_ashr_i32 s7, s6, 31
	s_add_u32 s28, s94, 0x1a300000
	s_addc_u32 s29, s95, 0
	v_lshlrev_b32_e32 v1, 3, v0
	s_add_u32 s12, s92, 0xaade000
	v_and_b32_e32 v80, 0x78, v1
	v_readlane_b32 s0, v239, 14
	s_addc_u32 s13, s93, 0
	v_ashrrev_i32_e32 v81, 4, v0
	v_and_b32_e32 v94, 15, v0
	v_bfe_u32 v95, v0, 4, 2
	v_mov_b32_e32 v83, 0
	v_lshlrev_b32_e32 v82, 2, v80
	v_readlane_b32 s1, v239, 15
	v_lshlrev_b32_e32 v0, 1, v80
	s_add_u32 s14, s92, 0xaede000
	v_lshl_add_u64 v[84:85], s[0:1], 0, v[82:83]
	s_mov_b32 s11, 0
	v_add_u32_e32 v96, 0, v0
	v_add_u32_e32 v97, s90, v0
	v_lshl_add_u64 v[86:87], s[48:49], 0, v[82:83]
	s_addc_u32 s15, s93, 0
	s_movk_i32 s30, 0x110
	v_mov_b32_e32 v98, 0x358637bd
	s_mov_b32 s31, 0x800000
	s_mov_b32 s33, 0xff800000
	v_mbcnt_hi_u32_b32 v99, -1, v217
	s_mov_b32 s34, s63
	s_mov_b32 s35, s63
	v_readlane_b32 s98, v240, 1
	s_cmpk_eq_u32 s98, 0x100
	s_cselect_b32 s99, 1, 0
	s_and_b32 s99, s99, s63
	s_and_b32 s99, s99, 1
	s_lshl_b32 s98, s99, 8
	s_add_i32 s35, s35, s98
	s_mov_b32 s34, s35
	s_mul_i32 s99, s99, 0x300
	s_cmp_lg_u32 s99, 0
	s_cselect_b32 s98, s35, -1
	s_nop 0
	s_nop 0
	s_nop 0
	s_nop 0
	s_nop 0
	s_nop 0
	s_nop 0
	s_nop 0
	s_nop 0
	s_nop 0
	s_nop 0
	s_nop 0
	s_nop 0
	s_nop 0
	s_branch .LBB0_597
.LBB0_596:
	v_readlane_b32 s0, v240, 1
	s_add_i32 s35, s35, s0
	s_cmpk_gt_i32 s35, 0x2ff
	s_cselect_b32 s1, s99, 0
	s_sub_i32 s35, s35, s1
	s_mov_b32 s34, s35
	v_readlane_b32 s1, v240, 2
	s_cmp_eq_u32 s35, s98
	s_cbranch_scc1 .LBB0_633
	s_cmpk_gt_i32 s35, 0x2ff
	s_cbranch_scc1 .LBB0_633

; __global__ void __launch_bounds__(NTHR, 2) fwd_megakernel(Params p) {
;     ...
;         { PHASE_IDS
;         for (int rep = 0; rep < REP_LIGHT * REP_MEM; ++rep)
;         for (int u = bx; u < 256 + 512; u += G) { if (u < 256) mem_unit<false>(p, l, lds, u, tid, wave, lane); else mem_unit<true>(p, l, lds, u - 256, tid, wave, lane); } }
.LBB0_2725:
	s_or_b64 exec, exec, s[0:1]
	v_readlane_b32 s0, v240, 14
	s_waitcnt lgkmcnt(0)
	v_mov_b32_e32 v0, v216
	v_readlane_b32 s1, v240, 15
	s_barrier
	s_and_b64 vcc, exec, s[0:1]
	v_readfirstlane_b32 s0, v0
	s_cbranch_vccnz .LBB0_2764
	s_cmp_lt_u32 s0, 64
	s_cselect_b64 s[6:7], -1, 0
	s_ashr_i32 s0, s0, 2
	s_and_b32 s4, s0, -16
	s_ashr_i32 s5, s4, 31
	v_lshlrev_b32_e32 v1, 3, v0
	s_add_u32 s12, s92, 0xaade000
	v_and_b32_e32 v80, 0x78, v1
	v_readlane_b32 s0, v239, 14
	s_addc_u32 s13, s93, 0
	v_ashrrev_i32_e32 v81, 4, v0
	s_waitcnt vmcnt(0)
	v_and_b32_e32 v94, 15, v0
	v_bfe_u32 v95, v0, 4, 2
	v_mov_b32_e32 v83, 0
	v_lshlrev_b32_e32 v82, 2, v80
	v_readlane_b32 s1, v239, 15
	v_lshlrev_b32_e32 v0, 1, v80
	s_add_u32 s14, s92, 0xaede000
	v_lshl_add_u64 v[84:85], s[0:1], 0, v[82:83]
	s_mov_b32 s11, 0
	v_add_u32_e32 v96, 0, v0
	v_add_u32_e32 v97, s90, v0
	v_lshl_add_u64 v[86:87], s[48:49], 0, v[82:83]
	s_addc_u32 s15, s93, 0
	s_movk_i32 s22, 0x110
	v_mov_b32_e32 v98, 0x358637bd
	s_mov_b32 s23, 0x800000
	s_mov_b32 s24, 0xff800000
	v_mbcnt_hi_u32_b32 v99, -1, v217
	s_mov_b32 s25, s63
	s_mov_b32 s26, s63
	v_readlane_b32 s98, v240, 1
	s_cmpk_eq_u32 s98, 0x100
	s_cselect_b32 s99, 1, 0
	s_and_b32 s99, s99, s63
	s_and_b32 s99, s99, 1
	s_lshl_b32 s98, s99, 8
	s_add_i32 s26, s26, s98
	s_mov_b32 s25, s26
	s_mul_i32 s99, s99, 0x300
	s_cmp_lg_u32 s99, 0
	s_cselect_b32 s98, s26, -1
	s_nop 0
	s_nop 0
	s_nop 0
	s_nop 0
	s_nop 0
	s_nop 0
	s_nop 0
	s_nop 0
	s_nop 0
	s_nop 0
	s_nop 0
	s_nop 0
	s_nop 0
	s_nop 0
	s_branch .LBB0_2728
.LBB0_2727:
	v_readlane_b32 s0, v240, 1
	s_add_i32 s26, s26, s0
	s_cmpk_gt_i32 s26, 0x2ff
	s_cselect_b32 s1, s99, 0
	s_sub_i32 s26, s26, s1
	s_mov_b32 s25, s26
	v_readlane_b32 s1, v240, 2
	s_cmp_eq_u32 s26, s98
	s_cbranch_scc1 .LBB0_2764
	s_cmpk_gt_i32 s26, 0x2ff
	s_cbranch_scc1 .LBB0_2764
